# v12 + grid seams: all waiting workgroups poll the top-level arrival counter against (gen+1)*nx instead of a generation word bumped by the last leader
# speedup vs baseline: 1.0028x; 1.0028x over previous
; __device__ __forceinline__ unsigned xb_ld(unsigned* p)              { return __hip_atomic_load(p, __ATOMIC_RELAXED, __HIP_MEMORY_SCOPE_AGENT); }
; __device__ __forceinline__ unsigned xb_add(unsigned* p, unsigned v) { return __hip_atomic_fetch_add(p, v, __ATOMIC_RELAXED, __HIP_MEMORY_SCOPE_AGENT); }
; #define XB_SPIN(cond, bar) do { unsigned _sp = 0; while (cond) { __builtin_amdgcn_s_sleep(1); \
;     if ((++_sp & 255u) == 0u) { if (xb_ld(&(bar)[XB_TMO])) break; if (_sp > XB_SPIN_CAP) { atomicAdd(&(bar)[XB_TMO], 1u); break; } } } } while (0)
; __device__ __forceinline__ void xcd_barrier(const XcdBarrier& b) {
;     ...
;         const unsigned old = xb_add(&bar[XB_XSUB(b.x)], 1u);
;         const unsigned gen = old / nloc;
;         if (old + 1u == (gen + 1u) * nloc) {
;             __builtin_amdgcn_fence(__ATOMIC_RELEASE, "agent");
;             asm volatile("s_waitcnt vmcnt(0)" ::: "memory");
;             const unsigned og = xb_add(&bar[XB_TOP], 1u);
;             const unsigned tg = og / nx;
;             if (og + 1u == (tg + 1u) * nx) xb_add(&bar[XB_TOPGEN], 1u);
;             else XB_SPIN(xb_ld(&bar[XB_TOPGEN]) == tg, bar);
;             __builtin_amdgcn_fence(__ATOMIC_ACQUIRE, "agent");
;             xb_add(&bar[XB_XGEN(b.x)], 1u);
;             asm volatile("s_waitcnt vmcnt(0)" ::: "memory");
;         } else {
;             XB_SPIN(xb_ld(&bar[XB_XGEN(b.x)]) == gen, bar);
.LBB0_144:
	s_or_b64 exec, exec, s[12:13]
	v_cvt_f32_u32_e32 v5, v3
	s_waitcnt vmcnt(0)
	v_readfirstlane_b32 s0, v4
	v_sub_u32_e32 v4, 0, v3
	v_rcp_iflag_f32_e32 v5, v5
	v_add_u32_e32 v6, s0, v2
	v_mul_f32_e32 v5, 0x4f7ffffe, v5
	v_cvt_u32_f32_e32 v5, v5
	v_mul_lo_u32 v2, v4, v5
	v_mul_hi_u32 v2, v5, v2
	v_add_u32_e32 v2, v5, v2
	v_mul_hi_u32 v2, v6, v2
	v_mul_lo_u32 v4, v2, v3
	v_sub_u32_e32 v4, v6, v4
	v_add_u32_e32 v5, 1, v2
	v_cmp_ge_u32_e32 vcc, v4, v3
	s_nop 1
	v_cndmask_b32_e32 v2, v2, v5, vcc
	v_sub_u32_e32 v5, v4, v3
	v_cndmask_b32_e32 v4, v4, v5, vcc
	v_add_u32_e32 v5, 1, v2
	v_cmp_ge_u32_e32 vcc, v4, v3
	v_add_u32_e32 v4, 1, v6
	s_nop 0
	v_cndmask_b32_e32 v2, v2, v5, vcc
	v_mul_lo_u32 v5, v3, v2
	v_add_u32_e32 v3, v5, v3
	v_cmp_ne_u32_e32 vcc, v4, v3
	s_and_saveexec_b64 s[0:1], vcc
	s_xor_b64 s[8:9], exec, s[0:1]
	s_cbranch_execz .LBB0_158
	s_waitcnt lgkmcnt(0)
	v_add_u32_e32 v5, 1, v2
	v_mul_lo_u32 v5, v5, v1
	v_mov_b32_e32 v1, 0
	s_add_u32 s16, s78, 0xbd03400
	s_addc_u32 s17, s79, 0
	global_load_dword v1, v1, s[16:17] sc1
	s_waitcnt vmcnt(0)
	v_cmp_lt_u32_e32 vcc, v1, v5
	s_and_saveexec_b64 s[12:13], vcc
	s_cbranch_execz .LBB0_157
	s_add_u32 s14, s78, 0xbd00200
	s_addc_u32 s15, s79, 0
	s_mov_b32 s0, 1
	s_mov_b64 s[18:19], 0
	v_mov_b32_e32 v1, 0
	s_branch .LBB0_148

; __device__ __forceinline__ unsigned xb_ld(unsigned* p)              { return __hip_atomic_load(p, __ATOMIC_RELAXED, __HIP_MEMORY_SCOPE_AGENT); }
; #define XB_SPIN(cond, bar) do { unsigned _sp = 0; while (cond) { __builtin_amdgcn_s_sleep(1); \
;     if ((++_sp & 255u) == 0u) { if (xb_ld(&(bar)[XB_TMO])) break; if (_sp > XB_SPIN_CAP) { atomicAdd(&(bar)[XB_TMO], 1u); break; } } } } while (0)
; __device__ __forceinline__ void xcd_barrier(const XcdBarrier& b) {
;     ...
;             XB_SPIN(xb_ld(&bar[XB_XGEN(b.x)]) == gen, bar);
.LBB0_150:
	global_load_dword v3, v1, s[16:17] sc1
	s_add_i32 s0, s0, 1
	s_mov_b64 s[24:25], -1
	s_waitcnt vmcnt(0)
	v_cmp_ge_u32_e32 vcc, v3, v5
	s_orn2_b64 s[22:23], vcc, exec
	s_branch .LBB0_147

; __device__ __forceinline__ unsigned xb_ld(unsigned* p)              { return __hip_atomic_load(p, __ATOMIC_RELAXED, __HIP_MEMORY_SCOPE_AGENT); }
; __device__ __forceinline__ unsigned xb_add(unsigned* p, unsigned v) { return __hip_atomic_fetch_add(p, v, __ATOMIC_RELAXED, __HIP_MEMORY_SCOPE_AGENT); }
; #define XB_SPIN(cond, bar) do { unsigned _sp = 0; while (cond) { __builtin_amdgcn_s_sleep(1); \
;     if ((++_sp & 255u) == 0u) { if (xb_ld(&(bar)[XB_TMO])) break; if (_sp > XB_SPIN_CAP) { atomicAdd(&(bar)[XB_TMO], 1u); break; } } } } while (0)
; __device__ __forceinline__ void xcd_barrier(const XcdBarrier& b) {
;     ...
;             const unsigned og = xb_add(&bar[XB_TOP], 1u);
;             const unsigned tg = og / nx;
;             if (og + 1u == (tg + 1u) * nx) xb_add(&bar[XB_TOPGEN], 1u);
;             else XB_SPIN(xb_ld(&bar[XB_TOPGEN]) == tg, bar);
.LBB0_161:
	s_or_b64 exec, exec, s[12:13]
	v_cvt_f32_u32_e32 v4, v1
	s_waitcnt vmcnt(0)
	v_readfirstlane_b32 s0, v3
	s_add_u32 s12, s78, 0xbd03500
	s_addc_u32 s13, s79, 0
	v_rcp_iflag_f32_e32 v4, v4
	v_add_u32_e32 v2, s0, v2
	v_add_u32_e32 v5, 1, v2
	s_mov_b64 s[14:15], -1
	v_mul_f32_e32 v3, 0x4f7ffffe, v4
	v_cvt_u32_f32_e32 v3, v3
	v_sub_u32_e32 v4, 0, v1
	v_mul_lo_u32 v4, v4, v3
	v_mul_hi_u32 v4, v3, v4
	v_add_u32_e32 v3, v3, v4
	v_mul_hi_u32 v3, v2, v3
	v_mul_lo_u32 v4, v3, v1
	v_sub_u32_e32 v2, v2, v4
	v_add_u32_e32 v6, 1, v3
	v_cmp_ge_u32_e32 vcc, v2, v1
	v_sub_u32_e32 v4, v2, v1
	s_nop 0
	v_cndmask_b32_e32 v3, v3, v6, vcc
	v_cndmask_b32_e32 v2, v2, v4, vcc
	v_add_u32_e32 v4, 1, v3
	v_cmp_ge_u32_e32 vcc, v2, v1
	s_nop 1
	v_cndmask_b32_e32 v4, v3, v4, vcc
	v_mul_lo_u32 v2, v1, v4
	v_add_u32_e32 v1, v2, v1
	v_mov_b32_e32 v6, v1
	v_cmp_ne_u32_e32 vcc, v5, v1
	v_mov_b64_e32 v[2:3], s[12:13]
	s_and_saveexec_b64 s[8:9], vcc
	s_cbranch_execz .LBB0_173
	v_mov_b32_e32 v1, 0
	global_load_dword v2, v1, s[12:13] offset:-256 sc1
	s_mov_b64 s[18:19], 0
	s_waitcnt vmcnt(0)
	v_cmp_lt_u32_e32 vcc, v2, v6
	s_and_saveexec_b64 s[16:17], vcc
	s_cbranch_execz .LBB0_172
	s_add_u32 s14, s78, 0xbd00200
	s_addc_u32 s15, s79, 0
	s_mov_b32 s0, 1
	s_branch .LBB0_165

; __device__ __forceinline__ unsigned xb_ld(unsigned* p)              { return __hip_atomic_load(p, __ATOMIC_RELAXED, __HIP_MEMORY_SCOPE_AGENT); }
; #define XB_SPIN(cond, bar) do { unsigned _sp = 0; while (cond) { __builtin_amdgcn_s_sleep(1); \
;     if ((++_sp & 255u) == 0u) { if (xb_ld(&(bar)[XB_TMO])) break; if (_sp > XB_SPIN_CAP) { atomicAdd(&(bar)[XB_TMO], 1u); break; } } } } while (0)
; __device__ __forceinline__ void xcd_barrier(const XcdBarrier& b) {
;     ...
;             else XB_SPIN(xb_ld(&bar[XB_TOPGEN]) == tg, bar);
.LBB0_167:
	global_load_dword v2, v1, s[12:13] offset:-256 sc1
	s_add_i32 s0, s0, 1
	s_mov_b64 s[22:23], -1
	s_waitcnt vmcnt(0)
	v_cmp_ge_u32_e32 vcc, v2, v6
	s_orn2_b64 s[26:27], vcc, exec
	s_branch .LBB0_164

; __device__ __forceinline__ unsigned xb_ld(unsigned* p)              { return __hip_atomic_load(p, __ATOMIC_RELAXED, __HIP_MEMORY_SCOPE_AGENT); }
; __device__ __forceinline__ unsigned xb_add(unsigned* p, unsigned v) { return __hip_atomic_fetch_add(p, v, __ATOMIC_RELAXED, __HIP_MEMORY_SCOPE_AGENT); }
; #define XB_SPIN(cond, bar) do { unsigned _sp = 0; while (cond) { __builtin_amdgcn_s_sleep(1); \
;     if ((++_sp & 255u) == 0u) { if (xb_ld(&(bar)[XB_TMO])) break; if (_sp > XB_SPIN_CAP) { atomicAdd(&(bar)[XB_TMO], 1u); break; } } } } while (0)
; __device__ __forceinline__ void xcd_barrier(const XcdBarrier& b) {
;     ...
;         const unsigned old = xb_add(&bar[XB_XSUB(b.x)], 1u);
;         const unsigned gen = old / nloc;
;         if (old + 1u == (gen + 1u) * nloc) {
;             __builtin_amdgcn_fence(__ATOMIC_RELEASE, "agent");
;             asm volatile("s_waitcnt vmcnt(0)" ::: "memory");
;             const unsigned og = xb_add(&bar[XB_TOP], 1u);
;             const unsigned tg = og / nx;
;             if (og + 1u == (tg + 1u) * nx) xb_add(&bar[XB_TOPGEN], 1u);
;             else XB_SPIN(xb_ld(&bar[XB_TOPGEN]) == tg, bar);
;             __builtin_amdgcn_fence(__ATOMIC_ACQUIRE, "agent");
;             xb_add(&bar[XB_XGEN(b.x)], 1u);
;             asm volatile("s_waitcnt vmcnt(0)" ::: "memory");
;         } else {
;             XB_SPIN(xb_ld(&bar[XB_XGEN(b.x)]) == gen, bar);
.LBB0_247:
	s_or_b64 exec, exec, s[22:23]
	v_cvt_f32_u32_e32 v6, v4
	s_waitcnt vmcnt(0)
	v_readfirstlane_b32 s0, v5
	v_sub_u32_e32 v5, 0, v4
	v_rcp_iflag_f32_e32 v6, v6
	v_add_u32_e32 v7, s0, v3
	v_mul_f32_e32 v6, 0x4f7ffffe, v6
	v_cvt_u32_f32_e32 v6, v6
	v_mul_lo_u32 v3, v5, v6
	v_mul_hi_u32 v3, v6, v3
	v_add_u32_e32 v3, v6, v3
	v_mul_hi_u32 v3, v7, v3
	v_mul_lo_u32 v5, v3, v4
	v_sub_u32_e32 v5, v7, v5
	v_add_u32_e32 v6, 1, v3
	v_cmp_ge_u32_e32 vcc, v5, v4
	s_nop 1
	v_cndmask_b32_e32 v3, v3, v6, vcc
	v_sub_u32_e32 v6, v5, v4
	v_cndmask_b32_e32 v5, v5, v6, vcc
	v_add_u32_e32 v6, 1, v3
	v_cmp_ge_u32_e32 vcc, v5, v4
	v_add_u32_e32 v5, 1, v7
	s_nop 0
	v_cndmask_b32_e32 v3, v3, v6, vcc
	v_mul_lo_u32 v6, v4, v3
	v_add_u32_e32 v4, v6, v4
	v_cmp_ne_u32_e32 vcc, v5, v4
	s_and_saveexec_b64 s[0:1], vcc
	s_xor_b64 s[20:21], exec, s[0:1]
	s_cbranch_execz .LBB0_261
	s_waitcnt lgkmcnt(0)
	v_add_u32_e32 v5, 1, v3
	v_mul_lo_u32 v5, v5, v2
	v_mov_b32_e32 v2, 0
	s_add_u32 s26, s78, 0xbd03400
	s_addc_u32 s27, s79, 0
	global_load_dword v2, v2, s[26:27] sc1
	s_waitcnt vmcnt(0)
	v_cmp_lt_u32_e32 vcc, v2, v5
	s_and_saveexec_b64 s[22:23], vcc
	s_cbranch_execz .LBB0_260
	s_add_u32 s24, s78, 0xbd00200
	s_addc_u32 s25, s79, 0
	s_mov_b32 s0, 1
	s_mov_b64 s[28:29], 0
	v_mov_b32_e32 v2, 0
	s_branch .LBB0_251

; __device__ __forceinline__ unsigned xb_ld(unsigned* p)              { return __hip_atomic_load(p, __ATOMIC_RELAXED, __HIP_MEMORY_SCOPE_AGENT); }
; #define XB_SPIN(cond, bar) do { unsigned _sp = 0; while (cond) { __builtin_amdgcn_s_sleep(1); \
;     if ((++_sp & 255u) == 0u) { if (xb_ld(&(bar)[XB_TMO])) break; if (_sp > XB_SPIN_CAP) { atomicAdd(&(bar)[XB_TMO], 1u); break; } } } } while (0)
; __device__ __forceinline__ void xcd_barrier(const XcdBarrier& b) {
;     ...
;             XB_SPIN(xb_ld(&bar[XB_XGEN(b.x)]) == gen, bar);
.LBB0_253:
	global_load_dword v4, v2, s[26:27] sc1
	s_add_i32 s0, s0, 1
	s_mov_b64 s[36:37], -1
	s_waitcnt vmcnt(0)
	v_cmp_ge_u32_e32 vcc, v4, v5
	s_orn2_b64 s[34:35], vcc, exec
	s_branch .LBB0_250

; __device__ __forceinline__ unsigned xb_ld(unsigned* p)              { return __hip_atomic_load(p, __ATOMIC_RELAXED, __HIP_MEMORY_SCOPE_AGENT); }
; __device__ __forceinline__ unsigned xb_add(unsigned* p, unsigned v) { return __hip_atomic_fetch_add(p, v, __ATOMIC_RELAXED, __HIP_MEMORY_SCOPE_AGENT); }
; #define XB_SPIN(cond, bar) do { unsigned _sp = 0; while (cond) { __builtin_amdgcn_s_sleep(1); \
;     if ((++_sp & 255u) == 0u) { if (xb_ld(&(bar)[XB_TMO])) break; if (_sp > XB_SPIN_CAP) { atomicAdd(&(bar)[XB_TMO], 1u); break; } } } } while (0)
; __device__ __forceinline__ void xcd_barrier(const XcdBarrier& b) {
;     ...
;             const unsigned og = xb_add(&bar[XB_TOP], 1u);
;             const unsigned tg = og / nx;
;             if (og + 1u == (tg + 1u) * nx) xb_add(&bar[XB_TOPGEN], 1u);
;             else XB_SPIN(xb_ld(&bar[XB_TOPGEN]) == tg, bar);
.LBB0_264:
	s_or_b64 exec, exec, s[22:23]
	v_cvt_f32_u32_e32 v5, v2
	s_waitcnt vmcnt(0)
	v_readfirstlane_b32 s0, v4
	s_add_u32 s22, s78, 0xbd03500
	s_addc_u32 s23, s79, 0
	v_rcp_iflag_f32_e32 v5, v5
	v_add_u32_e32 v3, s0, v3
	v_add_u32_e32 v6, 1, v3
	s_mov_b64 s[24:25], -1
	v_mul_f32_e32 v4, 0x4f7ffffe, v5
	v_cvt_u32_f32_e32 v4, v4
	v_sub_u32_e32 v5, 0, v2
	v_mul_lo_u32 v5, v5, v4
	v_mul_hi_u32 v5, v4, v5
	v_add_u32_e32 v4, v4, v5
	v_mul_hi_u32 v4, v3, v4
	v_mul_lo_u32 v5, v4, v2
	v_sub_u32_e32 v3, v3, v5
	v_add_u32_e32 v7, 1, v4
	v_cmp_ge_u32_e32 vcc, v3, v2
	v_sub_u32_e32 v5, v3, v2
	s_nop 0
	v_cndmask_b32_e32 v4, v4, v7, vcc
	v_cndmask_b32_e32 v3, v3, v5, vcc
	v_add_u32_e32 v5, 1, v4
	v_cmp_ge_u32_e32 vcc, v3, v2
	s_nop 1
	v_cndmask_b32_e32 v4, v4, v5, vcc
	v_mul_lo_u32 v3, v2, v4
	v_add_u32_e32 v2, v3, v2
	v_mov_b32_e32 v7, v2
	v_cmp_ne_u32_e32 vcc, v6, v2
	v_mov_b64_e32 v[2:3], s[22:23]
	s_and_saveexec_b64 s[20:21], vcc
	s_cbranch_execz .LBB0_276
	v_mov_b32_e32 v2, 0
	global_load_dword v3, v2, s[22:23] offset:-256 sc1
	s_mov_b64 s[28:29], 0
	s_waitcnt vmcnt(0)
	v_cmp_lt_u32_e32 vcc, v3, v7
	s_and_saveexec_b64 s[26:27], vcc
	s_cbranch_execz .LBB0_275
	s_add_u32 s24, s78, 0xbd00200
	s_addc_u32 s25, s79, 0
	s_mov_b32 s0, 1
	s_branch .LBB0_268

; __device__ __forceinline__ unsigned xb_ld(unsigned* p)              { return __hip_atomic_load(p, __ATOMIC_RELAXED, __HIP_MEMORY_SCOPE_AGENT); }
; #define XB_SPIN(cond, bar) do { unsigned _sp = 0; while (cond) { __builtin_amdgcn_s_sleep(1); \
;     if ((++_sp & 255u) == 0u) { if (xb_ld(&(bar)[XB_TMO])) break; if (_sp > XB_SPIN_CAP) { atomicAdd(&(bar)[XB_TMO], 1u); break; } } } } while (0)
; __device__ __forceinline__ void xcd_barrier(const XcdBarrier& b) {
;     ...
;             else XB_SPIN(xb_ld(&bar[XB_TOPGEN]) == tg, bar);
.LBB0_270:
	global_load_dword v3, v2, s[22:23] offset:-256 sc1
	s_add_i32 s0, s0, 1
	s_mov_b64 s[34:35], -1
	s_waitcnt vmcnt(0)
	v_cmp_ge_u32_e32 vcc, v3, v7
	s_orn2_b64 s[38:39], vcc, exec
	s_branch .LBB0_267

; __device__ __forceinline__ unsigned xb_ld(unsigned* p)              { return __hip_atomic_load(p, __ATOMIC_RELAXED, __HIP_MEMORY_SCOPE_AGENT); }
; __device__ __forceinline__ unsigned xb_add(unsigned* p, unsigned v) { return __hip_atomic_fetch_add(p, v, __ATOMIC_RELAXED, __HIP_MEMORY_SCOPE_AGENT); }
; #define XB_SPIN(cond, bar) do { unsigned _sp = 0; while (cond) { __builtin_amdgcn_s_sleep(1); \
;     if ((++_sp & 255u) == 0u) { if (xb_ld(&(bar)[XB_TMO])) break; if (_sp > XB_SPIN_CAP) { atomicAdd(&(bar)[XB_TMO], 1u); break; } } } } while (0)
; __device__ __forceinline__ void xcd_barrier(const XcdBarrier& b) {
;     ...
;         const unsigned old = xb_add(&bar[XB_XSUB(b.x)], 1u);
;         const unsigned gen = old / nloc;
;         if (old + 1u == (gen + 1u) * nloc) {
;             __builtin_amdgcn_fence(__ATOMIC_RELEASE, "agent");
;             asm volatile("s_waitcnt vmcnt(0)" ::: "memory");
;             const unsigned og = xb_add(&bar[XB_TOP], 1u);
;             const unsigned tg = og / nx;
;             if (og + 1u == (tg + 1u) * nx) xb_add(&bar[XB_TOPGEN], 1u);
;             else XB_SPIN(xb_ld(&bar[XB_TOPGEN]) == tg, bar);
;             __builtin_amdgcn_fence(__ATOMIC_ACQUIRE, "agent");
;             xb_add(&bar[XB_XGEN(b.x)], 1u);
;             asm volatile("s_waitcnt vmcnt(0)" ::: "memory");
;         } else {
;             XB_SPIN(xb_ld(&bar[XB_XGEN(b.x)]) == gen, bar);
.LBB0_438:
	s_or_b64 exec, exec, s[10:11]
	v_cvt_f32_u32_e32 v6, v4
	s_waitcnt vmcnt(0)
	v_readfirstlane_b32 s0, v5
	v_sub_u32_e32 v5, 0, v4
	v_rcp_iflag_f32_e32 v6, v6
	v_add_u32_e32 v7, s0, v3
	v_mul_f32_e32 v6, 0x4f7ffffe, v6
	v_cvt_u32_f32_e32 v6, v6
	v_mul_lo_u32 v3, v5, v6
	v_mul_hi_u32 v3, v6, v3
	v_add_u32_e32 v3, v6, v3
	v_mul_hi_u32 v3, v7, v3
	v_mul_lo_u32 v5, v3, v4
	v_sub_u32_e32 v5, v7, v5
	v_add_u32_e32 v6, 1, v3
	v_cmp_ge_u32_e32 vcc, v5, v4
	s_nop 1
	v_cndmask_b32_e32 v3, v3, v6, vcc
	v_sub_u32_e32 v6, v5, v4
	v_cndmask_b32_e32 v5, v5, v6, vcc
	v_add_u32_e32 v6, 1, v3
	v_cmp_ge_u32_e32 vcc, v5, v4
	v_add_u32_e32 v5, 1, v7
	s_nop 0
	v_cndmask_b32_e32 v3, v3, v6, vcc
	v_mul_lo_u32 v6, v4, v3
	v_add_u32_e32 v4, v6, v4
	v_cmp_ne_u32_e32 vcc, v5, v4
	s_and_saveexec_b64 s[0:1], vcc
	s_xor_b64 s[8:9], exec, s[0:1]
	s_cbranch_execz .LBB0_452
	s_waitcnt lgkmcnt(0)
	v_add_u32_e32 v5, 1, v3
	v_mul_lo_u32 v5, v5, v2
	v_mov_b32_e32 v2, 0
	s_add_u32 s14, s78, 0xbd03400
	s_addc_u32 s15, s79, 0
	global_load_dword v2, v2, s[14:15] sc1
	s_waitcnt vmcnt(0)
	v_cmp_lt_u32_e32 vcc, v2, v5
	s_and_saveexec_b64 s[10:11], vcc
	s_cbranch_execz .LBB0_451
	s_add_u32 s12, s78, 0xbd00200
	s_addc_u32 s13, s79, 0
	s_mov_b32 s0, 1
	s_mov_b64 s[16:17], 0
	v_mov_b32_e32 v2, 0
	s_branch .LBB0_442

; __device__ __forceinline__ unsigned xb_ld(unsigned* p)              { return __hip_atomic_load(p, __ATOMIC_RELAXED, __HIP_MEMORY_SCOPE_AGENT); }
; #define XB_SPIN(cond, bar) do { unsigned _sp = 0; while (cond) { __builtin_amdgcn_s_sleep(1); \
;     if ((++_sp & 255u) == 0u) { if (xb_ld(&(bar)[XB_TMO])) break; if (_sp > XB_SPIN_CAP) { atomicAdd(&(bar)[XB_TMO], 1u); break; } } } } while (0)
; __device__ __forceinline__ void xcd_barrier(const XcdBarrier& b) {
;     ...
;             XB_SPIN(xb_ld(&bar[XB_XGEN(b.x)]) == gen, bar);
.LBB0_444:
	global_load_dword v4, v2, s[14:15] sc1
	s_add_i32 s0, s0, 1
	s_mov_b64 s[22:23], -1
	s_waitcnt vmcnt(0)
	v_cmp_ge_u32_e32 vcc, v4, v5
	s_orn2_b64 s[20:21], vcc, exec
	s_branch .LBB0_441

; __device__ __forceinline__ unsigned xb_ld(unsigned* p)              { return __hip_atomic_load(p, __ATOMIC_RELAXED, __HIP_MEMORY_SCOPE_AGENT); }
; __device__ __forceinline__ unsigned xb_add(unsigned* p, unsigned v) { return __hip_atomic_fetch_add(p, v, __ATOMIC_RELAXED, __HIP_MEMORY_SCOPE_AGENT); }
; #define XB_SPIN(cond, bar) do { unsigned _sp = 0; while (cond) { __builtin_amdgcn_s_sleep(1); \
;     if ((++_sp & 255u) == 0u) { if (xb_ld(&(bar)[XB_TMO])) break; if (_sp > XB_SPIN_CAP) { atomicAdd(&(bar)[XB_TMO], 1u); break; } } } } while (0)
; __device__ __forceinline__ void xcd_barrier(const XcdBarrier& b) {
;     ...
;             const unsigned og = xb_add(&bar[XB_TOP], 1u);
;             const unsigned tg = og / nx;
;             if (og + 1u == (tg + 1u) * nx) xb_add(&bar[XB_TOPGEN], 1u);
;             else XB_SPIN(xb_ld(&bar[XB_TOPGEN]) == tg, bar);
.LBB0_455:
	s_or_b64 exec, exec, s[10:11]
	v_cvt_f32_u32_e32 v5, v2
	s_waitcnt vmcnt(0)
	v_readfirstlane_b32 s0, v4
	s_add_u32 s10, s78, 0xbd03500
	s_addc_u32 s11, s79, 0
	v_rcp_iflag_f32_e32 v5, v5
	v_add_u32_e32 v3, s0, v3
	v_add_u32_e32 v6, 1, v3
	s_mov_b64 s[12:13], -1
	v_mul_f32_e32 v4, 0x4f7ffffe, v5
	v_cvt_u32_f32_e32 v4, v4
	v_sub_u32_e32 v5, 0, v2
	v_mul_lo_u32 v5, v5, v4
	v_mul_hi_u32 v5, v4, v5
	v_add_u32_e32 v4, v4, v5
	v_mul_hi_u32 v4, v3, v4
	v_mul_lo_u32 v5, v4, v2
	v_sub_u32_e32 v3, v3, v5
	v_add_u32_e32 v7, 1, v4
	v_cmp_ge_u32_e32 vcc, v3, v2
	v_sub_u32_e32 v5, v3, v2
	s_nop 0
	v_cndmask_b32_e32 v4, v4, v7, vcc
	v_cndmask_b32_e32 v3, v3, v5, vcc
	v_add_u32_e32 v5, 1, v4
	v_cmp_ge_u32_e32 vcc, v3, v2
	s_nop 1
	v_cndmask_b32_e32 v4, v4, v5, vcc
	v_mul_lo_u32 v3, v2, v4
	v_add_u32_e32 v2, v3, v2
	v_mov_b32_e32 v7, v2
	v_cmp_ne_u32_e32 vcc, v6, v2
	v_mov_b64_e32 v[2:3], s[10:11]
	s_and_saveexec_b64 s[8:9], vcc
	s_cbranch_execz .LBB0_467
	v_mov_b32_e32 v2, 0
	global_load_dword v3, v2, s[10:11] offset:-256 sc1
	s_mov_b64 s[16:17], 0
	s_waitcnt vmcnt(0)
	v_cmp_lt_u32_e32 vcc, v3, v7
	s_and_saveexec_b64 s[14:15], vcc
	s_cbranch_execz .LBB0_466
	s_add_u32 s12, s78, 0xbd00200
	s_addc_u32 s13, s79, 0
	s_mov_b32 s0, 1
	s_branch .LBB0_459

; __device__ __forceinline__ unsigned xb_ld(unsigned* p)              { return __hip_atomic_load(p, __ATOMIC_RELAXED, __HIP_MEMORY_SCOPE_AGENT); }
; #define XB_SPIN(cond, bar) do { unsigned _sp = 0; while (cond) { __builtin_amdgcn_s_sleep(1); \
;     if ((++_sp & 255u) == 0u) { if (xb_ld(&(bar)[XB_TMO])) break; if (_sp > XB_SPIN_CAP) { atomicAdd(&(bar)[XB_TMO], 1u); break; } } } } while (0)
; __device__ __forceinline__ void xcd_barrier(const XcdBarrier& b) {
;     ...
;             else XB_SPIN(xb_ld(&bar[XB_TOPGEN]) == tg, bar);
.LBB0_461:
	global_load_dword v3, v2, s[10:11] offset:-256 sc1
	s_add_i32 s0, s0, 1
	s_mov_b64 s[20:21], -1
	s_waitcnt vmcnt(0)
	v_cmp_ge_u32_e32 vcc, v3, v7
	s_orn2_b64 s[24:25], vcc, exec
	s_branch .LBB0_458

; __device__ __forceinline__ unsigned xb_ld(unsigned* p)              { return __hip_atomic_load(p, __ATOMIC_RELAXED, __HIP_MEMORY_SCOPE_AGENT); }
; __device__ __forceinline__ unsigned xb_add(unsigned* p, unsigned v) { return __hip_atomic_fetch_add(p, v, __ATOMIC_RELAXED, __HIP_MEMORY_SCOPE_AGENT); }
; #define XB_SPIN(cond, bar) do { unsigned _sp = 0; while (cond) { __builtin_amdgcn_s_sleep(1); \
;     if ((++_sp & 255u) == 0u) { if (xb_ld(&(bar)[XB_TMO])) break; if (_sp > XB_SPIN_CAP) { atomicAdd(&(bar)[XB_TMO], 1u); break; } } } } while (0)
; __device__ __forceinline__ void xcd_barrier(const XcdBarrier& b) {
;     ...
;         const unsigned old = xb_add(&bar[XB_XSUB(b.x)], 1u);
;         const unsigned gen = old / nloc;
;         if (old + 1u == (gen + 1u) * nloc) {
;             __builtin_amdgcn_fence(__ATOMIC_RELEASE, "agent");
;             asm volatile("s_waitcnt vmcnt(0)" ::: "memory");
;             const unsigned og = xb_add(&bar[XB_TOP], 1u);
;             const unsigned tg = og / nx;
;             if (og + 1u == (tg + 1u) * nx) xb_add(&bar[XB_TOPGEN], 1u);
;             else XB_SPIN(xb_ld(&bar[XB_TOPGEN]) == tg, bar);
;             __builtin_amdgcn_fence(__ATOMIC_ACQUIRE, "agent");
;             xb_add(&bar[XB_XGEN(b.x)], 1u);
;             asm volatile("s_waitcnt vmcnt(0)" ::: "memory");
;         } else {
;             XB_SPIN(xb_ld(&bar[XB_XGEN(b.x)]) == gen, bar);
.LBB0_533:
	s_or_b64 exec, exec, s[12:13]
	v_cvt_f32_u32_e32 v132, v130
	s_waitcnt vmcnt(0)
	v_readfirstlane_b32 s4, v131
	v_sub_u32_e32 v131, 0, v130
	v_rcp_iflag_f32_e32 v132, v132
	v_add_u32_e32 v133, s4, v129
	v_mul_f32_e32 v132, 0x4f7ffffe, v132
	v_cvt_u32_f32_e32 v132, v132
	v_mul_lo_u32 v129, v131, v132
	v_mul_hi_u32 v129, v132, v129
	v_add_u32_e32 v129, v132, v129
	v_mul_hi_u32 v129, v133, v129
	v_mul_lo_u32 v131, v129, v130
	v_sub_u32_e32 v131, v133, v131
	v_add_u32_e32 v132, 1, v129
	v_cmp_ge_u32_e32 vcc, v131, v130
	s_nop 1
	v_cndmask_b32_e32 v129, v129, v132, vcc
	v_sub_u32_e32 v132, v131, v130
	v_cndmask_b32_e32 v131, v131, v132, vcc
	v_add_u32_e32 v132, 1, v129
	v_cmp_ge_u32_e32 vcc, v131, v130
	v_add_u32_e32 v131, 1, v133
	s_nop 0
	v_cndmask_b32_e32 v129, v129, v132, vcc
	v_mul_lo_u32 v132, v130, v129
	v_add_u32_e32 v130, v132, v130
	v_cmp_ne_u32_e32 vcc, v131, v130
	s_and_saveexec_b64 s[4:5], vcc
	s_xor_b64 s[4:5], exec, s[4:5]
	s_cbranch_execz .LBB0_547
	s_waitcnt lgkmcnt(0)
	v_add_u32_e32 v131, 1, v129
	v_mul_lo_u32 v131, v131, v128
	v_mov_b32_e32 v128, 0
	s_add_u32 s16, s78, 0xbd03400
	s_addc_u32 s17, s79, 0
	global_load_dword v128, v128, s[16:17] sc1
	s_waitcnt vmcnt(0)
	v_cmp_lt_u32_e32 vcc, v128, v131
	s_and_saveexec_b64 s[12:13], vcc
	s_cbranch_execz .LBB0_546
	s_add_u32 s14, s78, 0xbd00200
	s_addc_u32 s15, s79, 0
	s_mov_b32 s28, 1
	s_mov_b64 s[18:19], 0
	v_mov_b32_e32 v128, 0
	s_branch .LBB0_537

; __device__ __forceinline__ unsigned xb_ld(unsigned* p)              { return __hip_atomic_load(p, __ATOMIC_RELAXED, __HIP_MEMORY_SCOPE_AGENT); }
; #define XB_SPIN(cond, bar) do { unsigned _sp = 0; while (cond) { __builtin_amdgcn_s_sleep(1); \
;     if ((++_sp & 255u) == 0u) { if (xb_ld(&(bar)[XB_TMO])) break; if (_sp > XB_SPIN_CAP) { atomicAdd(&(bar)[XB_TMO], 1u); break; } } } } while (0)
; __device__ __forceinline__ void xcd_barrier(const XcdBarrier& b) {
;     ...
;             XB_SPIN(xb_ld(&bar[XB_XGEN(b.x)]) == gen, bar);
.LBB0_539:
	global_load_dword v130, v128, s[16:17] sc1
	s_add_i32 s28, s28, 1
	s_mov_b64 s[24:25], -1
	s_waitcnt vmcnt(0)
	v_cmp_ge_u32_e32 vcc, v130, v131
	s_orn2_b64 s[22:23], vcc, exec
	s_branch .LBB0_536

; __device__ __forceinline__ unsigned xb_ld(unsigned* p)              { return __hip_atomic_load(p, __ATOMIC_RELAXED, __HIP_MEMORY_SCOPE_AGENT); }
; __device__ __forceinline__ unsigned xb_add(unsigned* p, unsigned v) { return __hip_atomic_fetch_add(p, v, __ATOMIC_RELAXED, __HIP_MEMORY_SCOPE_AGENT); }
; #define XB_SPIN(cond, bar) do { unsigned _sp = 0; while (cond) { __builtin_amdgcn_s_sleep(1); \
;     if ((++_sp & 255u) == 0u) { if (xb_ld(&(bar)[XB_TMO])) break; if (_sp > XB_SPIN_CAP) { atomicAdd(&(bar)[XB_TMO], 1u); break; } } } } while (0)
; __device__ __forceinline__ void xcd_barrier(const XcdBarrier& b) {
;     ...
;             const unsigned og = xb_add(&bar[XB_TOP], 1u);
;             const unsigned tg = og / nx;
;             if (og + 1u == (tg + 1u) * nx) xb_add(&bar[XB_TOPGEN], 1u);
;             else XB_SPIN(xb_ld(&bar[XB_TOPGEN]) == tg, bar);
.LBB0_550:
	s_or_b64 exec, exec, s[12:13]
	v_cvt_f32_u32_e32 v131, v128
	s_waitcnt vmcnt(0)
	v_readfirstlane_b32 s4, v130
	s_add_u32 s12, s78, 0xbd03500
	s_addc_u32 s13, s79, 0
	v_rcp_iflag_f32_e32 v131, v131
	v_add_u32_e32 v129, s4, v129
	v_add_u32_e32 v132, 1, v129
	s_mov_b64 s[14:15], -1
	v_mul_f32_e32 v130, 0x4f7ffffe, v131
	v_cvt_u32_f32_e32 v130, v130
	v_sub_u32_e32 v131, 0, v128
	v_mul_lo_u32 v131, v131, v130
	v_mul_hi_u32 v131, v130, v131
	v_add_u32_e32 v130, v130, v131
	v_mul_hi_u32 v130, v129, v130
	v_mul_lo_u32 v131, v130, v128
	v_sub_u32_e32 v129, v129, v131
	v_add_u32_e32 v133, 1, v130
	v_cmp_ge_u32_e32 vcc, v129, v128
	v_sub_u32_e32 v131, v129, v128
	s_nop 0
	v_cndmask_b32_e32 v130, v130, v133, vcc
	v_cndmask_b32_e32 v129, v129, v131, vcc
	v_add_u32_e32 v131, 1, v130
	v_cmp_ge_u32_e32 vcc, v129, v128
	s_nop 1
	v_cndmask_b32_e32 v130, v130, v131, vcc
	v_mul_lo_u32 v129, v128, v130
	v_add_u32_e32 v128, v129, v128
	v_mov_b32_e32 v133, v128
	v_cmp_ne_u32_e32 vcc, v132, v128
	v_mov_b64_e32 v[128:129], s[12:13]
	s_and_saveexec_b64 s[4:5], vcc
	s_cbranch_execz .LBB0_562
	v_mov_b32_e32 v128, 0
	global_load_dword v129, v128, s[12:13] offset:-256 sc1
	s_mov_b64 s[18:19], 0
	s_waitcnt vmcnt(0)
	v_cmp_lt_u32_e32 vcc, v129, v133
	s_and_saveexec_b64 s[16:17], vcc
	s_cbranch_execz .LBB0_561
	s_add_u32 s14, s78, 0xbd00200
	s_addc_u32 s15, s79, 0
	s_mov_b32 s28, 1
	s_branch .LBB0_554

; __device__ __forceinline__ unsigned xb_ld(unsigned* p)              { return __hip_atomic_load(p, __ATOMIC_RELAXED, __HIP_MEMORY_SCOPE_AGENT); }
; #define XB_SPIN(cond, bar) do { unsigned _sp = 0; while (cond) { __builtin_amdgcn_s_sleep(1); \
;     if ((++_sp & 255u) == 0u) { if (xb_ld(&(bar)[XB_TMO])) break; if (_sp > XB_SPIN_CAP) { atomicAdd(&(bar)[XB_TMO], 1u); break; } } } } while (0)
; __device__ __forceinline__ void xcd_barrier(const XcdBarrier& b) {
;     ...
;             else XB_SPIN(xb_ld(&bar[XB_TOPGEN]) == tg, bar);
.LBB0_556:
	global_load_dword v129, v128, s[12:13] offset:-256 sc1
	s_add_i32 s28, s28, 1
	s_mov_b64 s[22:23], -1
	s_waitcnt vmcnt(0)
	v_cmp_ge_u32_e32 vcc, v129, v133
	s_orn2_b64 s[26:27], vcc, exec
	s_branch .LBB0_553
